# hand-written 2-deep pipelined weight converter (balanced rotation) replacing the compiler loop in the prologue only
# speedup vs baseline: 1.0064x; 1.0064x over previous
; #define LAS __attribute__((address_space(3)))
; __device__ __forceinline__ void tr_load(const float* src, int N, f32x4 (&v)[16], int lane) {
;     const int r4 = lane >> 4, c4 = (lane & 15) * 4;
; #pragma unroll
;     for (int i = 0; i < 16; ++i) v[i] = *(const f32x4*)(src + (size_t)(4 * i + r4) * N + c4);
; }
; __device__ __forceinline__ void tr_to_lds(const f32x4 (&v)[16], LAS float* scr, int lane) {
;     const int r4 = lane >> 4, c4 = (lane & 15) * 4;
; #pragma unroll
;     for (int i = 0; i < 16; ++i) { LAS float* s = scr + (4 * i + r4) * 65 + c4; s[0] = v[i].x; s[1] = v[i].y; s[2] = v[i].z; s[3] = v[i].w; }
;     LDS_WAIT(); asm volatile("" ::: "memory");
; }
; __device__ __forceinline__ void tr_store(bf16* dst, int K, const LAS float* scr, int lane) {
;     const int c = lane & 7;
; #pragma unroll
;     for (int j = 0; j < 8; ++j) { const int n = (lane >> 3) + 8 * j; const LAS float* s = scr + (8 * c) * 65 + n;
; __device__ __forceinline__ void convert_segments(const Args& args, unsigned char* ws, LAS unsigned char* lds, int seg_lo, int seg_hi, int part_lo, int part_hi, int nparts, int wid, int nw, int wave, int lane) {
;     LAS float* scr = (LAS float*)(lds + wave * 16640);
; #pragma unroll 1
;     for (int sI = seg_lo; sI < seg_hi; ++sI) {
;         const Seg sg = seg_at(sI);
;         const int nblk = sg.ncols / 64, nit = (sg.K / 64) * nblk;
;         const float* W = args.in[sg.in_idx] + (size_t)sg.src_l * sg.K * sg.N;
;         bf16* WT = (bf16*)(ws + WS_W + (size_t)sg.layer * LAYER_W + (size_t)sg.wsub_mib * MiB);
;         const int it_lo = (int)((long)nit * part_lo / nparts), it_hi = (int)((long)nit * part_hi / nparts);
;         int it = it_lo + wid;
;         f32x4 v[16];
;         if (it < it_hi) { const int kb = it / nblk, nb = it - kb * nblk; tr_load(W + (size_t)(64 * kb) * sg.N + sg.scol + 64 * nb, sg.N, v, lane); }
; #pragma unroll 1
;         for (; it < it_hi; it += nw) {
;             const int kb = it / nblk, nb = it - kb * nblk;
;             const int drow = sg.ilv ? (256 * (nb >> 1) + 64 * (nb & 1) + sg.drow) : (sg.drow + 64 * nb);
;             tr_to_lds(v, scr, lane);
;             const int itn = it + nw;
;             if (itn < it_hi) { const int kbn = itn / nblk, nbn = itn - kbn * nblk; tr_load(W + (size_t)(64 * kbn) * sg.N + sg.scol + 64 * nbn, sg.N, v, lane); }
.LBB0_11:
	s_or_b64 exec, exec, s[4:5]
	s_load_dwordx2 s[36:37], s[0:1], 0xf0
	v_readlane_b32 s4, v254, 0
	s_lshr_b32 s89, s3, 6
	s_lshl_b32 s4, s4, 3
	s_lshl_b32 s38, s88, 3
	s_add_i32 s40, s4, s89
	s_waitcnt lgkmcnt(0)
	s_cmp_lt_i32 s36, 1
	s_cselect_b64 s[4:5], -1, 0
	s_cmp_gt_i32 s37, 0
	s_cselect_b64 s[6:7], -1, 0
	s_and_b64 s[4:5], s[4:5], s[6:7]
	s_andn2_b64 vcc, exec, s[4:5]
	s_cbranch_vccnz .LBB0_49
	s_mov_b32 s62, s40
	s_mov_b32 s63, s38
	s_cmpk_eq_i32 s88, 0x100
	s_cselect_b32 s61, 23, 26
	s_cselect_b32 s71, 0x7ff, 0
	s_mov_b32 s70, 0
	v_mbcnt_lo_u32_b32 v160, -1, 0
	v_mbcnt_hi_u32_b32 v160, -1, v160
	v_lshrrev_b32_e32 v161, 4, v160
	v_and_b32_e32 v162, 15, v160
	v_lshlrev_b32_e32 v162, 2, v162
	s_mul_i32 s66, s89, 0x4100
	v_mul_u32_u24_e32 v163, 0x41, v161
	v_add_u32_e32 v163, v163, v162
	v_lshl_add_u32 v163, v163, 2, s66
	v_and_b32_e32 v164, 7, v160
	v_lshrrev_b32_e32 v165, 3, v160
	v_mul_u32_u24_e32 v166, 0x208, v164
	v_add_u32_e32 v166, v166, v165
	v_lshl_add_u32 v166, v166, 2, s66
	v_add_u32_e32 v167, 0x410, v166
	s_load_dwordx2 s[68:69], s[0:1], 0xe8
	s_mov_b32 s67, 0
cvp_seg:
	s_cmp_ge_u32 s70, s61
	s_cbranch_scc1 cvp_done
	s_mul_i32 s4, s70, 40
	s_getpc_b64 s[6:7]
	s_add_u32 s6, s6, __const._Z6seg_ati.segs@rel32@lo+4
	s_addc_u32 s7, s7, __const._Z6seg_ati.segs@rel32@hi+12
	s_add_u32 s6, s6, s4
	s_addc_u32 s7, s7, 0
	s_load_dwordx8 s[8:15], s[6:7], 0x0
	s_load_dwordx2 s[18:19], s[6:7], 0x20
	s_waitcnt lgkmcnt(0)
	s_lshr_b32 s20, s13, 6
	s_lshr_b32 s21, s11, 6
	s_mul_i32 s22, s20, s21
	s_lshl_b32 s4, s8, 3
	s_load_dwordx2 s[24:25], s[0:1], s4
	s_mul_i32 s5, s11, s10
	s_mul_i32 s5, s5, s9
	s_lshl_b32 s5, s5, 2
	s_lshl_b32 s6, s12, 2
	s_add_u32 s5, s5, s6
	s_waitcnt lgkmcnt(0)
	s_add_u32 s24, s24, s5
	s_addc_u32 s25, s25, 0
	s_mul_i32 s5, s14, 0x1a400000
	s_lshl_b32 s6, s15, 20
	s_add_u32 s5, s5, s6
	s_add_u32 s5, s5, 0x2d400000
	s_add_u32 s26, s68, s5
	s_addc_u32 s27, s69, 0
	s_mov_b32 s41, 0
	s_mov_b32 s42, s22
	s_add_i32 s43, s62, s67
	s_cmp_ge_u32 s43, s63
	s_cselect_b32 s4, s63, 0
	s_sub_i32 s43, s43, s4
	s_sub_i32 s4, s42, s41
	s_sub_i32 s67, s67, s4
	s_and_b32 s67, s67, s71
	s_add_i32 s43, s43, s41
	s_cmp_ge_i32 s43, s42
	s_cbranch_scc1 cvp_next
	v_cvt_f32_u32_e32 v170, s63
	v_cvt_f32_u32_e32 v171, s20
	v_rcp_f32_e32 v171, v171
	s_nop 1
	v_mul_f32_e32 v170, v170, v171
	v_cvt_u32_f32_e32 v170, v170
	s_nop 1
	v_readfirstlane_b32 s44, v170
	s_mul_i32 s72, s44, s20
	s_sub_i32 s45, s63, s72
	s_cmp_lt_i32 s45, 0
	s_cselect_b32 s72, s20, 0
	s_cselect_b32 s73, 1, 0
	s_add_i32 s45, s45, s72
	s_sub_i32 s44, s44, s73
	s_cmp_ge_i32 s45, s20
	s_cselect_b32 s72, s20, 0
	s_cselect_b32 s73, 1, 0
	s_sub_i32 s45, s45, s72
	s_add_i32 s44, s44, s73
	s_cmp_ge_i32 s45, s20
	s_cselect_b32 s72, s20, 0
	s_cselect_b32 s73, 1, 0
	s_sub_i32 s45, s45, s72
	s_add_i32 s44, s44, s73
	v_cvt_f32_u32_e32 v170, s43
	v_cvt_f32_u32_e32 v171, s20
	v_rcp_f32_e32 v171, v171
	s_nop 1
	v_mul_f32_e32 v170, v170, v171
	v_cvt_u32_f32_e32 v170, v170
	s_nop 1
	v_readfirstlane_b32 s46, v170
	s_mul_i32 s72, s46, s20
	s_sub_i32 s47, s43, s72
	s_cmp_lt_i32 s47, 0
	s_cselect_b32 s72, s20, 0
	s_cselect_b32 s73, 1, 0
	s_add_i32 s47, s47, s72
	s_sub_i32 s46, s46, s73
	s_cmp_ge_i32 s47, s20
	s_cselect_b32 s72, s20, 0
	s_cselect_b32 s73, 1, 0
	s_sub_i32 s47, s47, s72
	s_add_i32 s46, s46, s73
	s_cmp_ge_i32 s47, s20
	s_cselect_b32 s72, s20, 0
	s_cselect_b32 s73, 1, 0
	s_sub_i32 s47, s47, s72
	s_add_i32 s46, s46, s73
	v_mul_lo_u32 v168, v161, s10
	v_add_u32_e32 v168, v168, v162
	v_lshlrev_b32_e32 v168, 2, v168
	v_mul_lo_u32 v169, v165, s11
	v_lshl_add_u32 v169, v164, 3, v169
	v_lshlrev_b32_e32 v169, 1, v169
	s_lshl_b32 s48, s10, 4
	s_lshl_b32 s49, s11, 4
	s_mov_b32 s51, s43
	s_mov_b32 s52, s46
	s_mov_b32 s53, s47
	s_mov_b32 s50, s43
	s_mul_i32 s4, s46, s10
	s_add_i32 s4, s4, s47
	s_lshl_b32 s4, s4, 8
	s_add_u32 s56, s24, s4
	s_addc_u32 s57, s25, 0
	global_load_dwordx4 v[0:3], v168, s[56:57]
	s_add_u32 s56, s56, s48
	s_addc_u32 s57, s57, 0
	global_load_dwordx4 v[4:7], v168, s[56:57]
	s_add_u32 s56, s56, s48
	s_addc_u32 s57, s57, 0
	global_load_dwordx4 v[8:11], v168, s[56:57]
	s_add_u32 s56, s56, s48
	s_addc_u32 s57, s57, 0
	global_load_dwordx4 v[12:15], v168, s[56:57]
	s_add_u32 s56, s56, s48
	s_addc_u32 s57, s57, 0
	global_load_dwordx4 v[16:19], v168, s[56:57]
	s_add_u32 s56, s56, s48
	s_addc_u32 s57, s57, 0
	global_load_dwordx4 v[20:23], v168, s[56:57]
	s_add_u32 s56, s56, s48
	s_addc_u32 s57, s57, 0
	global_load_dwordx4 v[24:27], v168, s[56:57]
	s_add_u32 s56, s56, s48
	s_addc_u32 s57, s57, 0
	global_load_dwordx4 v[28:31], v168, s[56:57]
	s_add_u32 s56, s56, s48
	s_addc_u32 s57, s57, 0
	global_load_dwordx4 v[32:35], v168, s[56:57]
	s_add_u32 s56, s56, s48
	s_addc_u32 s57, s57, 0
	global_load_dwordx4 v[36:39], v168, s[56:57]
	s_add_u32 s56, s56, s48
	s_addc_u32 s57, s57, 0
	global_load_dwordx4 v[40:43], v168, s[56:57]
	s_add_u32 s56, s56, s48
	s_addc_u32 s57, s57, 0
	global_load_dwordx4 v[44:47], v168, s[56:57]
	s_add_u32 s56, s56, s48
	s_addc_u32 s57, s57, 0
	global_load_dwordx4 v[48:51], v168, s[56:57]
	s_add_u32 s56, s56, s48
	s_addc_u32 s57, s57, 0
	global_load_dwordx4 v[52:55], v168, s[56:57]
	s_add_u32 s56, s56, s48
	s_addc_u32 s57, s57, 0
	global_load_dwordx4 v[56:59], v168, s[56:57]
	s_add_u32 s56, s56, s48
	s_addc_u32 s57, s57, 0
	global_load_dwordx4 v[60:63], v168, s[56:57]
	s_add_i32 s50, s50, s63
	s_add_i32 s47, s47, s45
	s_add_i32 s46, s46, s44
	s_cmp_ge_u32 s47, s20
	s_cselect_b32 s4, s20, 0
	s_cselect_b32 s5, 1, 0
	s_sub_i32 s47, s47, s4
	s_add_i32 s46, s46, s5
	s_cmp_lt_i32 s50, s42
	s_cbranch_scc0 cvp_pre
; #define LAS __attribute__((address_space(3)))
; #define LDS_WAIT() asm volatile("s_waitcnt lgkmcnt(0)" ::: "memory")
; __device__ __forceinline__ void tr_load(const float* src, int N, f32x4 (&v)[16], int lane) {
;     const int r4 = lane >> 4, c4 = (lane & 15) * 4;
; #pragma unroll
;     for (int i = 0; i < 16; ++i) v[i] = *(const f32x4*)(src + (size_t)(4 * i + r4) * N + c4);
; }
; __device__ __forceinline__ void tr_to_lds(const f32x4 (&v)[16], LAS float* scr, int lane) {
;     const int r4 = lane >> 4, c4 = (lane & 15) * 4;
; #pragma unroll
;     for (int i = 0; i < 16; ++i) { LAS float* s = scr + (4 * i + r4) * 65 + c4; s[0] = v[i].x; s[1] = v[i].y; s[2] = v[i].z; s[3] = v[i].w; }
;     LDS_WAIT(); asm volatile("" ::: "memory");
; }
; __device__ __forceinline__ void convert_segments(const Args& args, unsigned char* ws, LAS unsigned char* lds, int seg_lo, int seg_hi, int part_lo, int part_hi, int nparts, int wid, int nw, int wave, int lane) {
;     ...
;         for (; it < it_hi; it += nw) {
;             const int kb = it / nblk, nb = it - kb * nblk;
;             const int drow = sg.ilv ? (256 * (nb >> 1) + 64 * (nb & 1) + sg.drow) : (sg.drow + 64 * nb);
;             tr_to_lds(v, scr, lane);
;             const int itn = it + nw;
;             if (itn < it_hi) { const int kbn = itn / nblk, nbn = itn - kbn * nblk; tr_load(W + (size_t)(64 * kbn) * sg.N + sg.scol + 64 * nbn, sg.N, v, lane); }
	s_mul_i32 s4, s46, s10
	s_add_i32 s4, s4, s47
	s_lshl_b32 s4, s4, 8
	s_add_u32 s56, s24, s4
	s_addc_u32 s57, s25, 0
	global_load_dwordx4 v[64:67], v168, s[56:57]
	s_add_u32 s56, s56, s48
	s_addc_u32 s57, s57, 0
	global_load_dwordx4 v[68:71], v168, s[56:57]
	s_add_u32 s56, s56, s48
	s_addc_u32 s57, s57, 0
	global_load_dwordx4 v[72:75], v168, s[56:57]
	s_add_u32 s56, s56, s48
	s_addc_u32 s57, s57, 0
	global_load_dwordx4 v[76:79], v168, s[56:57]
	s_add_u32 s56, s56, s48
	s_addc_u32 s57, s57, 0
	global_load_dwordx4 v[80:83], v168, s[56:57]
	s_add_u32 s56, s56, s48
	s_addc_u32 s57, s57, 0
	global_load_dwordx4 v[84:87], v168, s[56:57]
	s_add_u32 s56, s56, s48
	s_addc_u32 s57, s57, 0
	global_load_dwordx4 v[88:91], v168, s[56:57]
	s_add_u32 s56, s56, s48
	s_addc_u32 s57, s57, 0
	global_load_dwordx4 v[92:95], v168, s[56:57]
	s_add_u32 s56, s56, s48
	s_addc_u32 s57, s57, 0
	global_load_dwordx4 v[96:99], v168, s[56:57]
	s_add_u32 s56, s56, s48
	s_addc_u32 s57, s57, 0
	global_load_dwordx4 v[100:103], v168, s[56:57]
	s_add_u32 s56, s56, s48
	s_addc_u32 s57, s57, 0
	global_load_dwordx4 v[104:107], v168, s[56:57]
	s_add_u32 s56, s56, s48
	s_addc_u32 s57, s57, 0
	global_load_dwordx4 v[108:111], v168, s[56:57]
	s_add_u32 s56, s56, s48
	s_addc_u32 s57, s57, 0
	global_load_dwordx4 v[112:115], v168, s[56:57]
	s_add_u32 s56, s56, s48
	s_addc_u32 s57, s57, 0
	global_load_dwordx4 v[116:119], v168, s[56:57]
	s_add_u32 s56, s56, s48
	s_addc_u32 s57, s57, 0
	global_load_dwordx4 v[120:123], v168, s[56:57]
	s_add_u32 s56, s56, s48
	s_addc_u32 s57, s57, 0
	global_load_dwordx4 v[124:127], v168, s[56:57]
	s_add_i32 s50, s50, s63
	s_add_i32 s47, s47, s45
	s_add_i32 s46, s46, s44
	s_cmp_ge_u32 s47, s20
	s_cselect_b32 s4, s20, 0
	s_cselect_b32 s5, 1, 0
	s_sub_i32 s47, s47, s4
	s_add_i32 s46, s46, s5
cvp_pre:
	s_waitcnt vmcnt(0)
cvp_stepA:
	s_add_i32 s4, s51, s63
	s_cmp_lt_i32 s4, s42
	s_cbranch_scc0 cvp_w0A
	s_waitcnt vmcnt(32)
	s_branch cvp_goA
cvp_w0A:
	s_waitcnt vmcnt(0)
cvp_goA:
	ds_write_b32 v163, v0 offset:0
	ds_write_b32 v163, v1 offset:4
	ds_write_b32 v163, v2 offset:8
	ds_write_b32 v163, v3 offset:12
	ds_write_b32 v163, v4 offset:1040
	ds_write_b32 v163, v5 offset:1044
	ds_write_b32 v163, v6 offset:1048
	ds_write_b32 v163, v7 offset:1052
	ds_write_b32 v163, v8 offset:2080
	ds_write_b32 v163, v9 offset:2084
	ds_write_b32 v163, v10 offset:2088
	ds_write_b32 v163, v11 offset:2092
	ds_write_b32 v163, v12 offset:3120
	ds_write_b32 v163, v13 offset:3124
	ds_write_b32 v163, v14 offset:3128
	ds_write_b32 v163, v15 offset:3132
	ds_write_b32 v163, v16 offset:4160
	ds_write_b32 v163, v17 offset:4164
	ds_write_b32 v163, v18 offset:4168
	ds_write_b32 v163, v19 offset:4172
	ds_write_b32 v163, v20 offset:5200
	ds_write_b32 v163, v21 offset:5204
	ds_write_b32 v163, v22 offset:5208
	ds_write_b32 v163, v23 offset:5212
	ds_write_b32 v163, v24 offset:6240
	ds_write_b32 v163, v25 offset:6244
	ds_write_b32 v163, v26 offset:6248
	ds_write_b32 v163, v27 offset:6252
	ds_write_b32 v163, v28 offset:7280
	ds_write_b32 v163, v29 offset:7284
	ds_write_b32 v163, v30 offset:7288
	ds_write_b32 v163, v31 offset:7292
	ds_write_b32 v163, v32 offset:8320
	ds_write_b32 v163, v33 offset:8324
	ds_write_b32 v163, v34 offset:8328
	ds_write_b32 v163, v35 offset:8332
	ds_write_b32 v163, v36 offset:9360
	ds_write_b32 v163, v37 offset:9364
	ds_write_b32 v163, v38 offset:9368
	ds_write_b32 v163, v39 offset:9372
	ds_write_b32 v163, v40 offset:10400
	ds_write_b32 v163, v41 offset:10404
	ds_write_b32 v163, v42 offset:10408
	ds_write_b32 v163, v43 offset:10412
	ds_write_b32 v163, v44 offset:11440
	ds_write_b32 v163, v45 offset:11444
	ds_write_b32 v163, v46 offset:11448
	ds_write_b32 v163, v47 offset:11452
	ds_write_b32 v163, v48 offset:12480
	ds_write_b32 v163, v49 offset:12484
	ds_write_b32 v163, v50 offset:12488
	ds_write_b32 v163, v51 offset:12492
	ds_write_b32 v163, v52 offset:13520
	ds_write_b32 v163, v53 offset:13524
	ds_write_b32 v163, v54 offset:13528
	ds_write_b32 v163, v55 offset:13532
	ds_write_b32 v163, v56 offset:14560
	ds_write_b32 v163, v57 offset:14564
	ds_write_b32 v163, v58 offset:14568
	ds_write_b32 v163, v59 offset:14572
	ds_write_b32 v163, v60 offset:15600
	ds_write_b32 v163, v61 offset:15604
	ds_write_b32 v163, v62 offset:15608
	ds_write_b32 v163, v63 offset:15612
	s_waitcnt lgkmcnt(0)
	s_cmp_lt_i32 s50, s42
	s_cbranch_scc0 cvp_nlA
	s_mul_i32 s4, s46, s10
	s_add_i32 s4, s4, s47
	s_lshl_b32 s4, s4, 8
	s_add_u32 s56, s24, s4
	s_addc_u32 s57, s25, 0
	global_load_dwordx4 v[0:3], v168, s[56:57]
	s_add_u32 s56, s56, s48
	s_addc_u32 s57, s57, 0
	global_load_dwordx4 v[4:7], v168, s[56:57]
	s_add_u32 s56, s56, s48
	s_addc_u32 s57, s57, 0
	global_load_dwordx4 v[8:11], v168, s[56:57]
	s_add_u32 s56, s56, s48
	s_addc_u32 s57, s57, 0
	global_load_dwordx4 v[12:15], v168, s[56:57]
	s_add_u32 s56, s56, s48
	s_addc_u32 s57, s57, 0
	global_load_dwordx4 v[16:19], v168, s[56:57]
	s_add_u32 s56, s56, s48
	s_addc_u32 s57, s57, 0
	global_load_dwordx4 v[20:23], v168, s[56:57]
	s_add_u32 s56, s56, s48
	s_addc_u32 s57, s57, 0
	global_load_dwordx4 v[24:27], v168, s[56:57]
	s_add_u32 s56, s56, s48
	s_addc_u32 s57, s57, 0
	global_load_dwordx4 v[28:31], v168, s[56:57]
	s_add_u32 s56, s56, s48
	s_addc_u32 s57, s57, 0
	global_load_dwordx4 v[32:35], v168, s[56:57]
	s_add_u32 s56, s56, s48
	s_addc_u32 s57, s57, 0
	global_load_dwordx4 v[36:39], v168, s[56:57]
	s_add_u32 s56, s56, s48
	s_addc_u32 s57, s57, 0
	global_load_dwordx4 v[40:43], v168, s[56:57]
	s_add_u32 s56, s56, s48
	s_addc_u32 s57, s57, 0
	global_load_dwordx4 v[44:47], v168, s[56:57]
	s_add_u32 s56, s56, s48
	s_addc_u32 s57, s57, 0
	global_load_dwordx4 v[48:51], v168, s[56:57]
	s_add_u32 s56, s56, s48
	s_addc_u32 s57, s57, 0
	global_load_dwordx4 v[52:55], v168, s[56:57]
	s_add_u32 s56, s56, s48
	s_addc_u32 s57, s57, 0
	global_load_dwordx4 v[56:59], v168, s[56:57]
	s_add_u32 s56, s56, s48
	s_addc_u32 s57, s57, 0
	global_load_dwordx4 v[60:63], v168, s[56:57]
	s_add_i32 s50, s50, s63
	s_add_i32 s47, s47, s45
	s_add_i32 s46, s46, s44
	s_cmp_ge_u32 s47, s20
	s_cselect_b32 s4, s20, 0
	s_cselect_b32 s5, 1, 0
	s_sub_i32 s47, s47, s4
	s_add_i32 s46, s46, s5
; #define LAS __attribute__((address_space(3)))
; #define LDS_WAIT() asm volatile("s_waitcnt lgkmcnt(0)" ::: "memory")
; __device__ __forceinline__ unsigned pk2(float lo, float hi) { const f32x2c v = {lo, hi}; return __builtin_bit_cast(unsigned, __builtin_convertvector(v, bf16x2c)); }
; __device__ __forceinline__ void tr_store(bf16* dst, int K, const LAS float* scr, int lane) {
;     const int c = lane & 7;
; #pragma unroll
;     for (int j = 0; j < 8; ++j) { const int n = (lane >> 3) + 8 * j; const LAS float* s = scr + (8 * c) * 65 + n;
;         v4u o; o.x = pk2(s[0], s[65]); o.y = pk2(s[130], s[195]); o.z = pk2(s[260], s[325]); o.w = pk2(s[390], s[455]);
;         *(v4u*)(dst + (size_t)n * K + 8 * c) = o; }
;     LDS_WAIT(); asm volatile("" ::: "memory");
; }
; __device__ __forceinline__ void convert_segments(const Args& args, unsigned char* ws, LAS unsigned char* lds, int seg_lo, int seg_hi, int part_lo, int part_hi, int nparts, int wid, int nw, int wave, int lane) {
;     ...
;         for (; it < it_hi; it += nw) {
;             const int kb = it / nblk, nb = it - kb * nblk;
;             const int drow = sg.ilv ? (256 * (nb >> 1) + 64 * (nb & 1) + sg.drow) : (sg.drow + 64 * nb);
;             tr_to_lds(v, scr, lane);
;             const int itn = it + nw;
;             if (itn < it_hi) { const int kbn = itn / nblk, nbn = itn - kbn * nblk; tr_load(W + (size_t)(64 * kbn) * sg.N + sg.scol + 64 * nbn, sg.N, v, lane); }
;             tr_store(WT + (size_t)drow * sg.K + 64 * kb, sg.K, scr, lane);
cvp_nlA:
	s_lshr_b32 s4, s53, 1
	s_lshl_b32 s4, s4, 8
	s_and_b32 s5, s53, 1
	s_lshl_b32 s5, s5, 6
	s_add_i32 s4, s4, s5
	s_lshl_b32 s5, s53, 6
	s_cmp_lg_u32 s19, 0
	s_cselect_b32 s4, s4, s5
	s_add_i32 s4, s4, s18
	s_mul_i32 s4, s4, s11
	s_lshl_b32 s5, s52, 6
	s_add_i32 s4, s4, s5
	s_lshl_b32 s4, s4, 1
	s_add_u32 s54, s26, s4
	s_addc_u32 s55, s27, 0
	ds_read2_b32 v[128:129], v166 offset0:0 offset1:65
	ds_read2_b32 v[130:131], v166 offset0:130 offset1:195
	ds_read2_b32 v[132:133], v167 offset0:0 offset1:65
	ds_read2_b32 v[134:135], v167 offset0:130 offset1:195
	ds_read2_b32 v[136:137], v166 offset0:8 offset1:73
	ds_read2_b32 v[138:139], v166 offset0:138 offset1:203
	ds_read2_b32 v[140:141], v167 offset0:8 offset1:73
	ds_read2_b32 v[142:143], v167 offset0:138 offset1:203
	s_waitcnt lgkmcnt(4)
	v_cvt_pk_bf16_f32 v152, v128, v129
	v_cvt_pk_bf16_f32 v153, v130, v131
	v_cvt_pk_bf16_f32 v154, v132, v133
	v_cvt_pk_bf16_f32 v155, v134, v135
	global_store_dwordx4 v169, v[152:155], s[54:55]
	s_add_u32 s54, s54, s49
	s_addc_u32 s55, s55, 0
	ds_read2_b32 v[144:145], v166 offset0:16 offset1:81
	ds_read2_b32 v[146:147], v166 offset0:146 offset1:211
	ds_read2_b32 v[148:149], v167 offset0:16 offset1:81
	ds_read2_b32 v[150:151], v167 offset0:146 offset1:211
	s_waitcnt lgkmcnt(4)
	v_cvt_pk_bf16_f32 v156, v136, v137
	v_cvt_pk_bf16_f32 v157, v138, v139
	v_cvt_pk_bf16_f32 v158, v140, v141
	v_cvt_pk_bf16_f32 v159, v142, v143
	global_store_dwordx4 v169, v[156:159], s[54:55]
	s_add_u32 s54, s54, s49
	s_addc_u32 s55, s55, 0
	ds_read2_b32 v[128:129], v166 offset0:24 offset1:89
	ds_read2_b32 v[130:131], v166 offset0:154 offset1:219
	ds_read2_b32 v[132:133], v167 offset0:24 offset1:89
	ds_read2_b32 v[134:135], v167 offset0:154 offset1:219
	s_waitcnt lgkmcnt(4)
	v_cvt_pk_bf16_f32 v152, v144, v145
	v_cvt_pk_bf16_f32 v153, v146, v147
	v_cvt_pk_bf16_f32 v154, v148, v149
	v_cvt_pk_bf16_f32 v155, v150, v151
	global_store_dwordx4 v169, v[152:155], s[54:55]
	s_add_u32 s54, s54, s49
	s_addc_u32 s55, s55, 0
	ds_read2_b32 v[136:137], v166 offset0:32 offset1:97
	ds_read2_b32 v[138:139], v166 offset0:162 offset1:227
	ds_read2_b32 v[140:141], v167 offset0:32 offset1:97
	ds_read2_b32 v[142:143], v167 offset0:162 offset1:227
	s_waitcnt lgkmcnt(4)
	v_cvt_pk_bf16_f32 v156, v128, v129
	v_cvt_pk_bf16_f32 v157, v130, v131
	v_cvt_pk_bf16_f32 v158, v132, v133
	v_cvt_pk_bf16_f32 v159, v134, v135
	global_store_dwordx4 v169, v[156:159], s[54:55]
	s_add_u32 s54, s54, s49
	s_addc_u32 s55, s55, 0
	ds_read2_b32 v[144:145], v166 offset0:40 offset1:105
	ds_read2_b32 v[146:147], v166 offset0:170 offset1:235
	ds_read2_b32 v[148:149], v167 offset0:40 offset1:105
	ds_read2_b32 v[150:151], v167 offset0:170 offset1:235
	s_waitcnt lgkmcnt(4)
	v_cvt_pk_bf16_f32 v152, v136, v137
	v_cvt_pk_bf16_f32 v153, v138, v139
	v_cvt_pk_bf16_f32 v154, v140, v141
	v_cvt_pk_bf16_f32 v155, v142, v143
	global_store_dwordx4 v169, v[152:155], s[54:55]
	s_add_u32 s54, s54, s49
	s_addc_u32 s55, s55, 0
	ds_read2_b32 v[128:129], v166 offset0:48 offset1:113
	ds_read2_b32 v[130:131], v166 offset0:178 offset1:243
	ds_read2_b32 v[132:133], v167 offset0:48 offset1:113
	ds_read2_b32 v[134:135], v167 offset0:178 offset1:243
	s_waitcnt lgkmcnt(4)
	v_cvt_pk_bf16_f32 v156, v144, v145
	v_cvt_pk_bf16_f32 v157, v146, v147
	v_cvt_pk_bf16_f32 v158, v148, v149
	v_cvt_pk_bf16_f32 v159, v150, v151
	global_store_dwordx4 v169, v[156:159], s[54:55]
	s_add_u32 s54, s54, s49
	s_addc_u32 s55, s55, 0
	ds_read2_b32 v[136:137], v166 offset0:56 offset1:121
	ds_read2_b32 v[138:139], v166 offset0:186 offset1:251
	ds_read2_b32 v[140:141], v167 offset0:56 offset1:121
	ds_read2_b32 v[142:143], v167 offset0:186 offset1:251
	s_waitcnt lgkmcnt(4)
	v_cvt_pk_bf16_f32 v152, v128, v129
	v_cvt_pk_bf16_f32 v153, v130, v131
	v_cvt_pk_bf16_f32 v154, v132, v133
	v_cvt_pk_bf16_f32 v155, v134, v135
	global_store_dwordx4 v169, v[152:155], s[54:55]
	s_add_u32 s54, s54, s49
	s_addc_u32 s55, s55, 0
	s_waitcnt lgkmcnt(0)
	v_cvt_pk_bf16_f32 v156, v136, v137
	v_cvt_pk_bf16_f32 v157, v138, v139
	v_cvt_pk_bf16_f32 v158, v140, v141
	v_cvt_pk_bf16_f32 v159, v142, v143
	global_store_dwordx4 v169, v[156:159], s[54:55]
	s_add_i32 s51, s51, s63
	s_add_i32 s53, s53, s45
	s_add_i32 s52, s52, s44
	s_cmp_ge_u32 s53, s20
	s_cselect_b32 s4, s20, 0
	s_cselect_b32 s5, 1, 0
	s_sub_i32 s53, s53, s4
	s_add_i32 s52, s52, s5
	s_cmp_lt_i32 s51, s42
	s_cbranch_scc0 cvp_next
cvp_stepB:
	s_add_i32 s4, s51, s63
	s_cmp_lt_i32 s4, s42
	s_cbranch_scc0 cvp_w0B
	s_waitcnt vmcnt(32)
	s_branch cvp_goB
cvp_w0B:
	s_waitcnt vmcnt(0)
; #define LAS __attribute__((address_space(3)))
; #define LDS_WAIT() asm volatile("s_waitcnt lgkmcnt(0)" ::: "memory")
; __device__ __forceinline__ void tr_load(const float* src, int N, f32x4 (&v)[16], int lane) {
;     const int r4 = lane >> 4, c4 = (lane & 15) * 4;
; #pragma unroll
;     for (int i = 0; i < 16; ++i) v[i] = *(const f32x4*)(src + (size_t)(4 * i + r4) * N + c4);
; }
; __device__ __forceinline__ void tr_to_lds(const f32x4 (&v)[16], LAS float* scr, int lane) {
;     const int r4 = lane >> 4, c4 = (lane & 15) * 4;
; #pragma unroll
;     for (int i = 0; i < 16; ++i) { LAS float* s = scr + (4 * i + r4) * 65 + c4; s[0] = v[i].x; s[1] = v[i].y; s[2] = v[i].z; s[3] = v[i].w; }
;     LDS_WAIT(); asm volatile("" ::: "memory");
; }
; __device__ __forceinline__ void convert_segments(const Args& args, unsigned char* ws, LAS unsigned char* lds, int seg_lo, int seg_hi, int part_lo, int part_hi, int nparts, int wid, int nw, int wave, int lane) {
;     ...
;         for (; it < it_hi; it += nw) {
;             const int kb = it / nblk, nb = it - kb * nblk;
;             const int drow = sg.ilv ? (256 * (nb >> 1) + 64 * (nb & 1) + sg.drow) : (sg.drow + 64 * nb);
;             tr_to_lds(v, scr, lane);
;             const int itn = it + nw;
;             if (itn < it_hi) { const int kbn = itn / nblk, nbn = itn - kbn * nblk; tr_load(W + (size_t)(64 * kbn) * sg.N + sg.scol + 64 * nbn, sg.N, v, lane); }
cvp_goB:
	ds_write_b32 v163, v64 offset:0
	ds_write_b32 v163, v65 offset:4
	ds_write_b32 v163, v66 offset:8
	ds_write_b32 v163, v67 offset:12
	ds_write_b32 v163, v68 offset:1040
	ds_write_b32 v163, v69 offset:1044
	ds_write_b32 v163, v70 offset:1048
	ds_write_b32 v163, v71 offset:1052
	ds_write_b32 v163, v72 offset:2080
	ds_write_b32 v163, v73 offset:2084
	ds_write_b32 v163, v74 offset:2088
	ds_write_b32 v163, v75 offset:2092
	ds_write_b32 v163, v76 offset:3120
	ds_write_b32 v163, v77 offset:3124
	ds_write_b32 v163, v78 offset:3128
	ds_write_b32 v163, v79 offset:3132
	ds_write_b32 v163, v80 offset:4160
	ds_write_b32 v163, v81 offset:4164
	ds_write_b32 v163, v82 offset:4168
	ds_write_b32 v163, v83 offset:4172
	ds_write_b32 v163, v84 offset:5200
	ds_write_b32 v163, v85 offset:5204
	ds_write_b32 v163, v86 offset:5208
	ds_write_b32 v163, v87 offset:5212
	ds_write_b32 v163, v88 offset:6240
	ds_write_b32 v163, v89 offset:6244
	ds_write_b32 v163, v90 offset:6248
	ds_write_b32 v163, v91 offset:6252
	ds_write_b32 v163, v92 offset:7280
	ds_write_b32 v163, v93 offset:7284
	ds_write_b32 v163, v94 offset:7288
	ds_write_b32 v163, v95 offset:7292
	ds_write_b32 v163, v96 offset:8320
	ds_write_b32 v163, v97 offset:8324
	ds_write_b32 v163, v98 offset:8328
	ds_write_b32 v163, v99 offset:8332
	ds_write_b32 v163, v100 offset:9360
	ds_write_b32 v163, v101 offset:9364
	ds_write_b32 v163, v102 offset:9368
	ds_write_b32 v163, v103 offset:9372
	ds_write_b32 v163, v104 offset:10400
	ds_write_b32 v163, v105 offset:10404
	ds_write_b32 v163, v106 offset:10408
	ds_write_b32 v163, v107 offset:10412
	ds_write_b32 v163, v108 offset:11440
	ds_write_b32 v163, v109 offset:11444
	ds_write_b32 v163, v110 offset:11448
	ds_write_b32 v163, v111 offset:11452
	ds_write_b32 v163, v112 offset:12480
	ds_write_b32 v163, v113 offset:12484
	ds_write_b32 v163, v114 offset:12488
	ds_write_b32 v163, v115 offset:12492
	ds_write_b32 v163, v116 offset:13520
	ds_write_b32 v163, v117 offset:13524
	ds_write_b32 v163, v118 offset:13528
	ds_write_b32 v163, v119 offset:13532
	ds_write_b32 v163, v120 offset:14560
	ds_write_b32 v163, v121 offset:14564
	ds_write_b32 v163, v122 offset:14568
	ds_write_b32 v163, v123 offset:14572
	ds_write_b32 v163, v124 offset:15600
	ds_write_b32 v163, v125 offset:15604
	ds_write_b32 v163, v126 offset:15608
	ds_write_b32 v163, v127 offset:15612
	s_waitcnt lgkmcnt(0)
	s_cmp_lt_i32 s50, s42
	s_cbranch_scc0 cvp_nlB
	s_mul_i32 s4, s46, s10
	s_add_i32 s4, s4, s47
	s_lshl_b32 s4, s4, 8
	s_add_u32 s56, s24, s4
	s_addc_u32 s57, s25, 0
	global_load_dwordx4 v[64:67], v168, s[56:57]
	s_add_u32 s56, s56, s48
	s_addc_u32 s57, s57, 0
	global_load_dwordx4 v[68:71], v168, s[56:57]
	s_add_u32 s56, s56, s48
	s_addc_u32 s57, s57, 0
	global_load_dwordx4 v[72:75], v168, s[56:57]
	s_add_u32 s56, s56, s48
	s_addc_u32 s57, s57, 0
	global_load_dwordx4 v[76:79], v168, s[56:57]
	s_add_u32 s56, s56, s48
	s_addc_u32 s57, s57, 0
	global_load_dwordx4 v[80:83], v168, s[56:57]
	s_add_u32 s56, s56, s48
	s_addc_u32 s57, s57, 0
	global_load_dwordx4 v[84:87], v168, s[56:57]
	s_add_u32 s56, s56, s48
	s_addc_u32 s57, s57, 0
	global_load_dwordx4 v[88:91], v168, s[56:57]
	s_add_u32 s56, s56, s48
	s_addc_u32 s57, s57, 0
	global_load_dwordx4 v[92:95], v168, s[56:57]
	s_add_u32 s56, s56, s48
	s_addc_u32 s57, s57, 0
	global_load_dwordx4 v[96:99], v168, s[56:57]
	s_add_u32 s56, s56, s48
	s_addc_u32 s57, s57, 0
	global_load_dwordx4 v[100:103], v168, s[56:57]
	s_add_u32 s56, s56, s48
	s_addc_u32 s57, s57, 0
	global_load_dwordx4 v[104:107], v168, s[56:57]
	s_add_u32 s56, s56, s48
	s_addc_u32 s57, s57, 0
	global_load_dwordx4 v[108:111], v168, s[56:57]
	s_add_u32 s56, s56, s48
	s_addc_u32 s57, s57, 0
	global_load_dwordx4 v[112:115], v168, s[56:57]
	s_add_u32 s56, s56, s48
	s_addc_u32 s57, s57, 0
	global_load_dwordx4 v[116:119], v168, s[56:57]
	s_add_u32 s56, s56, s48
	s_addc_u32 s57, s57, 0
	global_load_dwordx4 v[120:123], v168, s[56:57]
	s_add_u32 s56, s56, s48
	s_addc_u32 s57, s57, 0
	global_load_dwordx4 v[124:127], v168, s[56:57]
	s_add_i32 s50, s50, s63
	s_add_i32 s47, s47, s45
	s_add_i32 s46, s46, s44
	s_cmp_ge_u32 s47, s20
	s_cselect_b32 s4, s20, 0
	s_cselect_b32 s5, 1, 0
	s_sub_i32 s47, s47, s4
	s_add_i32 s46, s46, s5
; #define LAS __attribute__((address_space(3)))
; #define LDS_WAIT() asm volatile("s_waitcnt lgkmcnt(0)" ::: "memory")
; __device__ __forceinline__ unsigned pk2(float lo, float hi) { const f32x2c v = {lo, hi}; return __builtin_bit_cast(unsigned, __builtin_convertvector(v, bf16x2c)); }
; __device__ __forceinline__ void tr_store(bf16* dst, int K, const LAS float* scr, int lane) {
;     const int c = lane & 7;
; #pragma unroll
;     for (int j = 0; j < 8; ++j) { const int n = (lane >> 3) + 8 * j; const LAS float* s = scr + (8 * c) * 65 + n;
;         v4u o; o.x = pk2(s[0], s[65]); o.y = pk2(s[130], s[195]); o.z = pk2(s[260], s[325]); o.w = pk2(s[390], s[455]);
;         *(v4u*)(dst + (size_t)n * K + 8 * c) = o; }
;     LDS_WAIT(); asm volatile("" ::: "memory");
; }
; __device__ __forceinline__ void convert_segments(const Args& args, unsigned char* ws, LAS unsigned char* lds, int seg_lo, int seg_hi, int part_lo, int part_hi, int nparts, int wid, int nw, int wave, int lane) {
;     ...
;         for (; it < it_hi; it += nw) {
;             const int kb = it / nblk, nb = it - kb * nblk;
;             const int drow = sg.ilv ? (256 * (nb >> 1) + 64 * (nb & 1) + sg.drow) : (sg.drow + 64 * nb);
;             tr_to_lds(v, scr, lane);
;             const int itn = it + nw;
;             if (itn < it_hi) { const int kbn = itn / nblk, nbn = itn - kbn * nblk; tr_load(W + (size_t)(64 * kbn) * sg.N + sg.scol + 64 * nbn, sg.N, v, lane); }
;             tr_store(WT + (size_t)drow * sg.K + 64 * kb, sg.K, scr, lane);
;         }
;     }
; }
cvp_nlB:
	s_lshr_b32 s4, s53, 1
	s_lshl_b32 s4, s4, 8
	s_and_b32 s5, s53, 1
	s_lshl_b32 s5, s5, 6
	s_add_i32 s4, s4, s5
	s_lshl_b32 s5, s53, 6
	s_cmp_lg_u32 s19, 0
	s_cselect_b32 s4, s4, s5
	s_add_i32 s4, s4, s18
	s_mul_i32 s4, s4, s11
	s_lshl_b32 s5, s52, 6
	s_add_i32 s4, s4, s5
	s_lshl_b32 s4, s4, 1
	s_add_u32 s54, s26, s4
	s_addc_u32 s55, s27, 0
	ds_read2_b32 v[128:129], v166 offset0:0 offset1:65
	ds_read2_b32 v[130:131], v166 offset0:130 offset1:195
	ds_read2_b32 v[132:133], v167 offset0:0 offset1:65
	ds_read2_b32 v[134:135], v167 offset0:130 offset1:195
	ds_read2_b32 v[136:137], v166 offset0:8 offset1:73
	ds_read2_b32 v[138:139], v166 offset0:138 offset1:203
	ds_read2_b32 v[140:141], v167 offset0:8 offset1:73
	ds_read2_b32 v[142:143], v167 offset0:138 offset1:203
	s_waitcnt lgkmcnt(4)
	v_cvt_pk_bf16_f32 v152, v128, v129
	v_cvt_pk_bf16_f32 v153, v130, v131
	v_cvt_pk_bf16_f32 v154, v132, v133
	v_cvt_pk_bf16_f32 v155, v134, v135
	global_store_dwordx4 v169, v[152:155], s[54:55]
	s_add_u32 s54, s54, s49
	s_addc_u32 s55, s55, 0
	ds_read2_b32 v[144:145], v166 offset0:16 offset1:81
	ds_read2_b32 v[146:147], v166 offset0:146 offset1:211
	ds_read2_b32 v[148:149], v167 offset0:16 offset1:81
	ds_read2_b32 v[150:151], v167 offset0:146 offset1:211
	s_waitcnt lgkmcnt(4)
	v_cvt_pk_bf16_f32 v156, v136, v137
	v_cvt_pk_bf16_f32 v157, v138, v139
	v_cvt_pk_bf16_f32 v158, v140, v141
	v_cvt_pk_bf16_f32 v159, v142, v143
	global_store_dwordx4 v169, v[156:159], s[54:55]
	s_add_u32 s54, s54, s49
	s_addc_u32 s55, s55, 0
	ds_read2_b32 v[128:129], v166 offset0:24 offset1:89
	ds_read2_b32 v[130:131], v166 offset0:154 offset1:219
	ds_read2_b32 v[132:133], v167 offset0:24 offset1:89
	ds_read2_b32 v[134:135], v167 offset0:154 offset1:219
	s_waitcnt lgkmcnt(4)
	v_cvt_pk_bf16_f32 v152, v144, v145
	v_cvt_pk_bf16_f32 v153, v146, v147
	v_cvt_pk_bf16_f32 v154, v148, v149
	v_cvt_pk_bf16_f32 v155, v150, v151
	global_store_dwordx4 v169, v[152:155], s[54:55]
	s_add_u32 s54, s54, s49
	s_addc_u32 s55, s55, 0
	ds_read2_b32 v[136:137], v166 offset0:32 offset1:97
	ds_read2_b32 v[138:139], v166 offset0:162 offset1:227
	ds_read2_b32 v[140:141], v167 offset0:32 offset1:97
	ds_read2_b32 v[142:143], v167 offset0:162 offset1:227
	s_waitcnt lgkmcnt(4)
	v_cvt_pk_bf16_f32 v156, v128, v129
	v_cvt_pk_bf16_f32 v157, v130, v131
	v_cvt_pk_bf16_f32 v158, v132, v133
	v_cvt_pk_bf16_f32 v159, v134, v135
	global_store_dwordx4 v169, v[156:159], s[54:55]
	s_add_u32 s54, s54, s49
	s_addc_u32 s55, s55, 0
	ds_read2_b32 v[144:145], v166 offset0:40 offset1:105
	ds_read2_b32 v[146:147], v166 offset0:170 offset1:235
	ds_read2_b32 v[148:149], v167 offset0:40 offset1:105
	ds_read2_b32 v[150:151], v167 offset0:170 offset1:235
	s_waitcnt lgkmcnt(4)
	v_cvt_pk_bf16_f32 v152, v136, v137
	v_cvt_pk_bf16_f32 v153, v138, v139
	v_cvt_pk_bf16_f32 v154, v140, v141
	v_cvt_pk_bf16_f32 v155, v142, v143
	global_store_dwordx4 v169, v[152:155], s[54:55]
	s_add_u32 s54, s54, s49
	s_addc_u32 s55, s55, 0
	ds_read2_b32 v[128:129], v166 offset0:48 offset1:113
	ds_read2_b32 v[130:131], v166 offset0:178 offset1:243
	ds_read2_b32 v[132:133], v167 offset0:48 offset1:113
	ds_read2_b32 v[134:135], v167 offset0:178 offset1:243
	s_waitcnt lgkmcnt(4)
	v_cvt_pk_bf16_f32 v156, v144, v145
	v_cvt_pk_bf16_f32 v157, v146, v147
	v_cvt_pk_bf16_f32 v158, v148, v149
	v_cvt_pk_bf16_f32 v159, v150, v151
	global_store_dwordx4 v169, v[156:159], s[54:55]
	s_add_u32 s54, s54, s49
	s_addc_u32 s55, s55, 0
	ds_read2_b32 v[136:137], v166 offset0:56 offset1:121
	ds_read2_b32 v[138:139], v166 offset0:186 offset1:251
	ds_read2_b32 v[140:141], v167 offset0:56 offset1:121
	ds_read2_b32 v[142:143], v167 offset0:186 offset1:251
	s_waitcnt lgkmcnt(4)
	v_cvt_pk_bf16_f32 v152, v128, v129
	v_cvt_pk_bf16_f32 v153, v130, v131
	v_cvt_pk_bf16_f32 v154, v132, v133
	v_cvt_pk_bf16_f32 v155, v134, v135
	global_store_dwordx4 v169, v[152:155], s[54:55]
	s_add_u32 s54, s54, s49
	s_addc_u32 s55, s55, 0
	s_waitcnt lgkmcnt(0)
	v_cvt_pk_bf16_f32 v156, v136, v137
	v_cvt_pk_bf16_f32 v157, v138, v139
	v_cvt_pk_bf16_f32 v158, v140, v141
	v_cvt_pk_bf16_f32 v159, v142, v143
	global_store_dwordx4 v169, v[156:159], s[54:55]
	s_add_i32 s51, s51, s63
	s_add_i32 s53, s53, s45
	s_add_i32 s52, s52, s44
	s_cmp_ge_u32 s53, s20
	s_cselect_b32 s4, s20, 0
	s_cselect_b32 s5, 1, 0
	s_sub_i32 s53, s53, s4
	s_add_i32 s52, s52, s5
	s_cmp_lt_i32 s51, s42
	s_cbranch_scc0 cvp_next
	s_branch cvp_stepA
cvp_next:
	s_add_i32 s70, s70, 1
	s_branch cvp_seg
cvp_done:
	s_waitcnt vmcnt(0) lgkmcnt(0)
	s_mov_b64 s[12:13], 0
	s_load_dwordx2 s[14:15], s[0:1], 0xe8
	s_mul_i32 s4, s89, 0x4100
	v_mbcnt_lo_u32_b32 v65, -1, 0
	v_mbcnt_hi_u32_b32 v65, -1, v65
	s_mov_b32 s21, 0
	v_lshlrev_b32_e32 v0, 3, v65
	s_waitcnt lgkmcnt(0)
	s_add_u32 s5, s14, s12
	s_addc_u32 s6, s15, s13
	s_cmpk_eq_i32 s88, 0x100
	s_cselect_b32 s19, 23, 26
	s_add_i32 s4, s4, 0
	s_add_u32 s24, s5, 0x2d400000
	v_ashrrev_i32_e32 v66, 4, v65
	v_lshlrev_b32_e32 v64, 2, v65
	s_movk_i32 s5, 0x104
	v_ashrrev_i32_e32 v102, 3, v65
	v_and_b32_e32 v0, 56, v0
	v_and_b32_e32 v68, 60, v64
	v_mul_lo_u32 v2, v66, s5
	v_mul_u32_u24_e32 v3, 0x104, v0
	v_lshlrev_b32_e32 v4, 2, v102
	v_readlane_b32 s5, v254, 0
	s_addc_u32 s25, s6, 0
	v_lshl_add_u32 v1, v68, 2, s4
	v_add3_u32 v67, s4, v3, v4
	s_lshl_b32 s27, s5, 9
	s_lshl_b32 s4, s89, 6
	s_add_i32 s27, s27, s4
	s_lshl_b32 s39, s5, 10
	s_lshl_b32 s4, s89, 7
	v_mov_b32_e32 v71, 0
	v_add_u32_e32 v72, 4, v66
	v_add_u32_e32 v74, 8, v66
	v_add_u32_e32 v76, 12, v66
	v_add_u32_e32 v78, 16, v66
	v_add_u32_e32 v80, 20, v66
	v_add_u32_e32 v82, 24, v66
	v_add_u32_e32 v84, 28, v66
	v_add_u32_e32 v86, 32, v66
	v_add_u32_e32 v88, 36, v66
	v_add_u32_e32 v90, 40, v66
	v_add_u32_e32 v92, 44, v66
	v_add_u32_e32 v94, 48, v66
	v_add_u32_e32 v96, 52, v66
	v_add_u32_e32 v98, 56, v66
	v_add_u32_e32 v100, 60, v66
	v_add_u32_e32 v104, 8, v102
	v_add_u32_e32 v106, 16, v102
	v_add_u32_e32 v108, 24, v102
	v_add_u32_e32 v110, 32, v102
	v_add_u32_e32 v112, 40, v102
	v_add_u32_e32 v114, 48, v102
	v_add_u32_e32 v116, 56, v102
	s_ashr_i32 s41, s40, 31
	s_abs_i32 s26, s40
	s_lshl_b32 s18, s88, 9
	s_add_i32 s39, s39, s4
	s_lshl_b32 s42, s88, 10
	v_add_u32_e32 v69, v1, v2
	v_lshlrev_b32_e32 v70, 1, v0
	s_mov_b32 s43, 0
	s_mov_b32 s99, 0
	s_branch .LBB0_28
